# FF1 K-loop: second global->register staging set (prefetch two K-tiles ahead)
# baseline (speedup 1.0000x reference)
; #define MFMA(a, b, c) __builtin_amdgcn_mfma_f32_32x32x16_f16(__builtin_bit_cast(h16x8, (a)), __builtin_bit_cast(h16x8, (b)), (c), 0, 0, 0)
; template <int MODE, bool BIG = false> DI void gemm_tile(const Params& p, int tm, int tn, int kv, char* smem) {
;     ...
;     char* Bs2 = smem + 256 * 80;
;     uint4 ra[4], rb[2];
; #pragma unroll
;     for (int i = 0; i < 4; ++i) { const int id = tid + 256 * i; ra[i] = load_a<MODE>(p, tma, kv, id >> 2, 0, id & 3); }
; #pragma unroll
;     for (int i = 0; i < 2; ++i) { const int id = tid + 256 * i; rb[i] = load_b<MODE>(p, tn, kv, id >> 2, 0, id & 3); }
;     for (int kt = 0; kt < 2 * KT; ++kt) {
;       __syncthreads();
; #pragma unroll
;       for (int i = 0; i < 4; ++i) { const int id = tid + 256 * i; *(uint4*)(As + (id >> 2) * 80 + (id & 3) * 16) = ra[i]; }
; #pragma unroll
;       for (int i = 0; i < 2; ++i) { const int id = tid + 256 * i; *(uint4*)(Bs2 + (id >> 2) * 80 + (id & 3) * 16) = rb[i]; }
;       __syncthreads();
;       if (kt + 1 < 2 * KT) {
;         const int k1 = kt + 1;
; #pragma unroll
;         for (int i = 0; i < 4; ++i) { const int id = tid + 256 * i; ra[i] = load_a<MODE>(p, tma, kv, id >> 2, k1 >> 1, ((k1 & 1) << 2) | (id & 3)); }
; #pragma unroll
;         for (int i = 0; i < 2; ++i) { const int id = tid + 256 * i; rb[i] = load_b<MODE>(p, tn, kv, id >> 2, k1 >> 1, ((k1 & 1) << 2) | (id & 3)); }
;       }
;       {
;         bf16x8 af[2][4], bfr[2][2];
; #pragma unroll
;         for (int s = 0; s < 2; ++s) {
; #pragma unroll
;           for (int i = 0; i < 4; ++i) af[s][i] = *(const bf16x8*)(As + (wm * 128 + i * 32 + r) * 80 + s * 32 + hf * 16);
; #pragma unroll
;           for (int j = 0; j < 2; ++j) bfr[s][j] = *(const bf16x8*)(Bs2 + (wn * 64 + j * 32 + r) * 80 + s * 32 + hf * 16);
;         }
;         __builtin_amdgcn_s_setprio(1);
; #pragma unroll
;         for (int s = 0; s < 2; ++s)
; #pragma unroll
;           for (int i = 0; i < 4; ++i)
; #pragma unroll
;             for (int j = 0; j < 2; ++j) acc[i][j] = MFMA(af[s][i], bfr[s][j], acc[i][j]);
;         __builtin_amdgcn_s_setprio(0);
;       }
;     }
.LBB0_978:
	s_barrier
	s_waitcnt vmcnt(5)
	ds_write_b128 v175, v[132:135]
	s_waitcnt vmcnt(4)
	ds_write_b128 v174, v[128:131]
	s_waitcnt vmcnt(3)
	ds_write_b128 v177, v[140:143]
	s_waitcnt vmcnt(2)
	ds_write_b128 v176, v[136:139]
	s_waitcnt vmcnt(1)
	ds_write_b128 v175, v[148:151] offset:20480
	s_waitcnt vmcnt(0)
	ds_write_b128 v174, v[144:147] offset:20480
	s_and_b32 s15, s7, 0x7c0
	s_lshl_b32 s15, s15, 1
	v_and_or_b32 v228, s6, 4, v178
	s_add_u32 s16, s22, s15
	v_lshlrev_b32_e32 v152, 4, v228
	s_addc_u32 s17, s23, 0
	v_lshl_add_u64 v[228:229], s[16:17], 0, v[152:153]
	s_add_u32 s16, s0, s15
	v_lshl_add_u64 v[230:231], v[228:229], 0, v[154:155]
	v_lshl_add_u64 v[236:237], v[228:229], 0, v[156:157]
	v_lshl_add_u64 v[238:239], v[228:229], 0, v[158:159]
	v_lshl_add_u64 v[244:245], v[228:229], 0, v[160:161]
	s_addc_u32 s17, s1, 0
	global_load_dwordx4 v[232:235], v[230:231], off
	s_nop 0
	global_load_dwordx4 v[228:231], v[236:237], off
	global_load_dwordx4 v[240:243], v[238:239], off
	s_nop 0
	global_load_dwordx4 v[236:239], v[244:245], off
	v_lshl_add_u64 v[244:245], s[16:17], 0, v[152:153]
	v_lshl_add_u64 v[246:247], v[244:245], 0, v[162:163]
	v_lshl_add_u64 v[244:245], v[244:245], 0, v[164:165]
	global_load_dwordx4 v[248:251], v[246:247], off
	s_nop 0
	global_load_dwordx4 v[244:247], v[244:245], off
	s_add_i32 s6, s6, 4
	s_add_i32 s7, s7, 32
	s_and_b32 s15, s7, 0x7c0
	s_lshl_b32 s15, s15, 1
	v_and_or_b32 v128, s6, 4, v178
	s_add_u32 s16, s22, s15
	v_lshlrev_b32_e32 v152, 4, v128
	s_addc_u32 s17, s23, 0
	v_lshl_add_u64 v[128:129], s[16:17], 0, v[152:153]
	s_add_u32 s16, s0, s15
	v_lshl_add_u64 v[130:131], v[128:129], 0, v[154:155]
	v_lshl_add_u64 v[136:137], v[128:129], 0, v[156:157]
	v_lshl_add_u64 v[138:139], v[128:129], 0, v[158:159]
	v_lshl_add_u64 v[144:145], v[128:129], 0, v[160:161]
	s_addc_u32 s17, s1, 0
	global_load_dwordx4 v[132:135], v[130:131], off
	s_nop 0
	global_load_dwordx4 v[128:131], v[136:137], off
	global_load_dwordx4 v[140:143], v[138:139], off
	s_nop 0
	global_load_dwordx4 v[136:139], v[144:145], off
	v_lshl_add_u64 v[144:145], s[16:17], 0, v[152:153]
	v_lshl_add_u64 v[146:147], v[144:145], 0, v[162:163]
	v_lshl_add_u64 v[144:145], v[144:145], 0, v[164:165]
	global_load_dwordx4 v[148:151], v[146:147], off
	s_nop 0
	global_load_dwordx4 v[144:147], v[144:145], off
	s_add_i32 s6, s6, 4
	s_add_i32 s7, s7, 32
	s_waitcnt lgkmcnt(0)
	s_barrier
	ds_read_b128 v[180:183], v170
	ds_read_b128 v[188:191], v170 offset:2560
	ds_read_b128 v[196:199], v170 offset:5120
	ds_read_b128 v[204:207], v172
	ds_read_b128 v[212:215], v171 offset:20480
	ds_read_b128 v[220:223], v171 offset:23040
.Lgk_ff1_loop:
	ds_read_b128 v[184:187], v170 offset:32
	ds_read_b128 v[192:195], v170 offset:2592
	ds_read_b128 v[200:203], v170 offset:5152
	ds_read_b128 v[208:211], v172 offset:32
	ds_read_b128 v[216:219], v171 offset:20512
	ds_read_b128 v[224:227], v171 offset:23072
	s_setprio 1
	s_waitcnt lgkmcnt(6)
	v_mfma_f32_32x32x16_f16 v[112:127], v[180:183], v[212:215], v[112:127]
	s_waitcnt vmcnt(11)
	ds_write_b128 v175, v[232:235] offset:32768
	v_mfma_f32_32x32x16_f16 v[96:111], v[180:183], v[220:223], v[96:111]
	s_waitcnt vmcnt(10)
	ds_write_b128 v174, v[228:231] offset:32768
	v_mfma_f32_32x32x16_f16 v[80:95], v[188:191], v[212:215], v[80:95]
	s_waitcnt vmcnt(9)
	ds_write_b128 v177, v[240:243] offset:32768
	v_mfma_f32_32x32x16_f16 v[64:79], v[188:191], v[220:223], v[64:79]
	s_waitcnt vmcnt(8)
	ds_write_b128 v176, v[236:239] offset:32768
	v_mfma_f32_32x32x16_f16 v[48:63], v[196:199], v[212:215], v[48:63]
	s_waitcnt vmcnt(7)
	ds_write_b128 v175, v[248:251] offset:53248
	v_mfma_f32_32x32x16_f16 v[32:47], v[196:199], v[220:223], v[32:47]
	s_waitcnt vmcnt(6)
	ds_write_b128 v174, v[244:247] offset:53248
	v_mfma_f32_32x32x16_f16 v[16:31], v[204:207], v[212:215], v[16:31]
	s_and_b32 s15, s7, 0x7c0
	s_lshl_b32 s15, s15, 1
	v_and_or_b32 v228, s6, 4, v178
	s_add_u32 s16, s22, s15
	v_lshlrev_b32_e32 v152, 4, v228
	s_addc_u32 s17, s23, 0
	v_lshl_add_u64 v[228:229], s[16:17], 0, v[152:153]
	s_add_u32 s16, s0, s15
	v_lshl_add_u64 v[230:231], v[228:229], 0, v[154:155]
	v_lshl_add_u64 v[236:237], v[228:229], 0, v[156:157]
	v_mfma_f32_32x32x16_f16 v[0:15], v[204:207], v[220:223], v[0:15]
	v_lshl_add_u64 v[238:239], v[228:229], 0, v[158:159]
	v_lshl_add_u64 v[244:245], v[228:229], 0, v[160:161]
	s_addc_u32 s17, s1, 0
	global_load_dwordx4 v[232:235], v[230:231], off
	s_nop 0
	global_load_dwordx4 v[228:231], v[236:237], off
	global_load_dwordx4 v[240:243], v[238:239], off
	s_nop 0
	global_load_dwordx4 v[236:239], v[244:245], off
	v_lshl_add_u64 v[244:245], s[16:17], 0, v[152:153]
	v_lshl_add_u64 v[246:247], v[244:245], 0, v[162:163]
	v_lshl_add_u64 v[244:245], v[244:245], 0, v[164:165]
	global_load_dwordx4 v[248:251], v[246:247], off
	s_nop 0
	global_load_dwordx4 v[244:247], v[244:245], off
	s_add_i32 s6, s6, 4
	s_add_i32 s7, s7, 32
	s_waitcnt lgkmcnt(0)
	s_barrier
; #define MFMA(a, b, c) __builtin_amdgcn_mfma_f32_32x32x16_f16(__builtin_bit_cast(h16x8, (a)), __builtin_bit_cast(h16x8, (b)), (c), 0, 0, 0)
; template <int MODE, bool BIG = false> DI void gemm_tile(const Params& p, int tm, int tn, int kv, char* smem) {
;     ...
;     for (int kt = 0; kt < 2 * KT; ++kt) {
;       __syncthreads();
; #pragma unroll
;       for (int i = 0; i < 4; ++i) { const int id = tid + 256 * i; *(uint4*)(As + (id >> 2) * 80 + (id & 3) * 16) = ra[i]; }
; #pragma unroll
;       for (int i = 0; i < 2; ++i) { const int id = tid + 256 * i; *(uint4*)(Bs2 + (id >> 2) * 80 + (id & 3) * 16) = rb[i]; }
;       __syncthreads();
;       if (kt + 1 < 2 * KT) {
;         const int k1 = kt + 1;
; #pragma unroll
;         for (int i = 0; i < 4; ++i) { const int id = tid + 256 * i; ra[i] = load_a<MODE>(p, tma, kv, id >> 2, k1 >> 1, ((k1 & 1) << 2) | (id & 3)); }
; #pragma unroll
;         for (int i = 0; i < 2; ++i) { const int id = tid + 256 * i; rb[i] = load_b<MODE>(p, tn, kv, id >> 2, k1 >> 1, ((k1 & 1) << 2) | (id & 3)); }
;       }
;       {
;         bf16x8 af[2][4], bfr[2][2];
; #pragma unroll
;         for (int s = 0; s < 2; ++s) {
; #pragma unroll
;           for (int i = 0; i < 4; ++i) af[s][i] = *(const bf16x8*)(As + (wm * 128 + i * 32 + r) * 80 + s * 32 + hf * 16);
; #pragma unroll
;           for (int j = 0; j < 2; ++j) bfr[s][j] = *(const bf16x8*)(Bs2 + (wn * 64 + j * 32 + r) * 80 + s * 32 + hf * 16);
;         }
;         __builtin_amdgcn_s_setprio(1);
; #pragma unroll
;         for (int s = 0; s < 2; ++s)
; #pragma unroll
;           for (int i = 0; i < 4; ++i)
; #pragma unroll
;             for (int j = 0; j < 2; ++j) acc[i][j] = MFMA(af[s][i], bfr[s][j], acc[i][j]);
;         __builtin_amdgcn_s_setprio(0);
;       }
;     }
	ds_read_b128 v[180:183], v170 offset:32768
	ds_read_b128 v[188:191], v170 offset:35328
	ds_read_b128 v[196:199], v170 offset:37888
	ds_read_b128 v[204:207], v172 offset:32768
	ds_read_b128 v[212:215], v171 offset:53248
	ds_read_b128 v[220:223], v171 offset:55808
	v_mfma_f32_32x32x16_f16 v[112:127], v[184:187], v[216:219], v[112:127]
	v_mfma_f32_32x32x16_f16 v[96:111], v[184:187], v[224:227], v[96:111]
	v_mfma_f32_32x32x16_f16 v[80:95], v[192:195], v[216:219], v[80:95]
	v_mfma_f32_32x32x16_f16 v[64:79], v[192:195], v[224:227], v[64:79]
	v_mfma_f32_32x32x16_f16 v[48:63], v[200:203], v[216:219], v[48:63]
	v_mfma_f32_32x32x16_f16 v[32:47], v[200:203], v[224:227], v[32:47]
	v_mfma_f32_32x32x16_f16 v[16:31], v[208:211], v[216:219], v[16:31]
	v_mfma_f32_32x32x16_f16 v[0:15], v[208:211], v[224:227], v[0:15]
	s_setprio 0
	ds_read_b128 v[184:187], v170 offset:32800
	ds_read_b128 v[192:195], v170 offset:35360
	ds_read_b128 v[200:203], v170 offset:37920
	ds_read_b128 v[208:211], v172 offset:32800
	ds_read_b128 v[216:219], v171 offset:53280
	ds_read_b128 v[224:227], v171 offset:55840
	s_setprio 1
	s_waitcnt lgkmcnt(6)
	v_mfma_f32_32x32x16_f16 v[112:127], v[180:183], v[212:215], v[112:127]
	s_waitcnt vmcnt(11)
	ds_write_b128 v175, v[132:135]
	v_mfma_f32_32x32x16_f16 v[96:111], v[180:183], v[220:223], v[96:111]
	s_waitcnt vmcnt(10)
	ds_write_b128 v174, v[128:131]
	v_mfma_f32_32x32x16_f16 v[80:95], v[188:191], v[212:215], v[80:95]
	s_waitcnt vmcnt(9)
	ds_write_b128 v177, v[140:143]
	v_mfma_f32_32x32x16_f16 v[64:79], v[188:191], v[220:223], v[64:79]
	s_waitcnt vmcnt(8)
	ds_write_b128 v176, v[136:139]
	v_mfma_f32_32x32x16_f16 v[48:63], v[196:199], v[212:215], v[48:63]
	s_waitcnt vmcnt(7)
	ds_write_b128 v175, v[148:151] offset:20480
	v_mfma_f32_32x32x16_f16 v[32:47], v[196:199], v[220:223], v[32:47]
	s_waitcnt vmcnt(6)
	ds_write_b128 v174, v[144:147] offset:20480
	v_mfma_f32_32x32x16_f16 v[16:31], v[204:207], v[212:215], v[16:31]
	s_and_b32 s15, s7, 0x7c0
	s_lshl_b32 s15, s15, 1
	v_and_or_b32 v128, s6, 4, v178
	s_add_u32 s16, s22, s15
	v_lshlrev_b32_e32 v152, 4, v128
	s_addc_u32 s17, s23, 0
	v_lshl_add_u64 v[128:129], s[16:17], 0, v[152:153]
	s_add_u32 s16, s0, s15
	v_lshl_add_u64 v[130:131], v[128:129], 0, v[154:155]
	v_lshl_add_u64 v[136:137], v[128:129], 0, v[156:157]
	v_mfma_f32_32x32x16_f16 v[0:15], v[204:207], v[220:223], v[0:15]
	v_lshl_add_u64 v[138:139], v[128:129], 0, v[158:159]
	v_lshl_add_u64 v[144:145], v[128:129], 0, v[160:161]
	s_addc_u32 s17, s1, 0
	global_load_dwordx4 v[132:135], v[130:131], off
	s_nop 0
	global_load_dwordx4 v[128:131], v[136:137], off
	global_load_dwordx4 v[140:143], v[138:139], off
	s_nop 0
	global_load_dwordx4 v[136:139], v[144:145], off
	v_lshl_add_u64 v[144:145], s[16:17], 0, v[152:153]
	v_lshl_add_u64 v[146:147], v[144:145], 0, v[162:163]
	v_lshl_add_u64 v[144:145], v[144:145], 0, v[164:165]
	global_load_dwordx4 v[148:151], v[146:147], off
	s_nop 0
	global_load_dwordx4 v[144:147], v[144:145], off
	s_add_i32 s6, s6, 4
	s_add_i32 s7, s7, 32
	s_waitcnt lgkmcnt(0)
	s_barrier
	ds_read_b128 v[180:183], v170
	ds_read_b128 v[188:191], v170 offset:2560
	ds_read_b128 v[196:199], v170 offset:5120
	ds_read_b128 v[204:207], v172
	ds_read_b128 v[212:215], v171 offset:20480
	ds_read_b128 v[220:223], v171 offset:23040
	v_mfma_f32_32x32x16_f16 v[112:127], v[184:187], v[216:219], v[112:127]
	v_mfma_f32_32x32x16_f16 v[96:111], v[184:187], v[224:227], v[96:111]
	v_mfma_f32_32x32x16_f16 v[80:95], v[192:195], v[216:219], v[80:95]
	v_mfma_f32_32x32x16_f16 v[64:79], v[192:195], v[224:227], v[64:79]
	v_mfma_f32_32x32x16_f16 v[48:63], v[200:203], v[216:219], v[48:63]
	v_mfma_f32_32x32x16_f16 v[32:47], v[200:203], v[224:227], v[32:47]
	v_mfma_f32_32x32x16_f16 v[16:31], v[208:211], v[216:219], v[16:31]
	v_mfma_f32_32x32x16_f16 v[0:15], v[208:211], v[224:227], v[0:15]
	s_setprio 0
	s_cmpk_eq_i32 s6, 0x7c
	s_cbranch_scc0 .Lgk_ff1_loop
	ds_read_b128 v[184:187], v170 offset:32
	ds_read_b128 v[192:195], v170 offset:2592
	ds_read_b128 v[200:203], v170 offset:5152
	ds_read_b128 v[208:211], v172 offset:32
	ds_read_b128 v[216:219], v171 offset:20512
	ds_read_b128 v[224:227], v171 offset:23072
	s_setprio 1
	s_waitcnt lgkmcnt(6)
	v_mfma_f32_32x32x16_f16 v[112:127], v[180:183], v[212:215], v[112:127]
	s_waitcnt vmcnt(11)
	ds_write_b128 v175, v[232:235] offset:32768
	v_mfma_f32_32x32x16_f16 v[96:111], v[180:183], v[220:223], v[96:111]
	s_waitcnt vmcnt(10)
	ds_write_b128 v174, v[228:231] offset:32768
	v_mfma_f32_32x32x16_f16 v[80:95], v[188:191], v[212:215], v[80:95]
	s_waitcnt vmcnt(9)
	ds_write_b128 v177, v[240:243] offset:32768
	v_mfma_f32_32x32x16_f16 v[64:79], v[188:191], v[220:223], v[64:79]
	s_waitcnt vmcnt(8)
	ds_write_b128 v176, v[236:239] offset:32768
	v_mfma_f32_32x32x16_f16 v[48:63], v[196:199], v[212:215], v[48:63]
	s_waitcnt vmcnt(7)
	ds_write_b128 v175, v[248:251] offset:53248
	v_mfma_f32_32x32x16_f16 v[32:47], v[196:199], v[220:223], v[32:47]
	s_waitcnt vmcnt(6)
	ds_write_b128 v174, v[244:247] offset:53248
	v_mfma_f32_32x32x16_f16 v[16:31], v[204:207], v[212:215], v[16:31]
	s_and_b32 s15, s7, 0x7c0
	s_lshl_b32 s15, s15, 1
	v_and_or_b32 v228, s6, 4, v178
	s_add_u32 s16, s22, s15
	v_lshlrev_b32_e32 v152, 4, v228
	s_addc_u32 s17, s23, 0
	v_lshl_add_u64 v[228:229], s[16:17], 0, v[152:153]
	s_add_u32 s16, s0, s15
	v_lshl_add_u64 v[230:231], v[228:229], 0, v[154:155]
	v_lshl_add_u64 v[236:237], v[228:229], 0, v[156:157]
	v_mfma_f32_32x32x16_f16 v[0:15], v[204:207], v[220:223], v[0:15]
	v_lshl_add_u64 v[238:239], v[228:229], 0, v[158:159]
	v_lshl_add_u64 v[244:245], v[228:229], 0, v[160:161]
	s_addc_u32 s17, s1, 0
	global_load_dwordx4 v[232:235], v[230:231], off
	s_nop 0
	global_load_dwordx4 v[228:231], v[236:237], off
	global_load_dwordx4 v[240:243], v[238:239], off
	s_nop 0
	global_load_dwordx4 v[236:239], v[244:245], off
	v_lshl_add_u64 v[244:245], s[16:17], 0, v[152:153]
	v_lshl_add_u64 v[246:247], v[244:245], 0, v[162:163]
	v_lshl_add_u64 v[244:245], v[244:245], 0, v[164:165]
	global_load_dwordx4 v[248:251], v[246:247], off
	s_nop 0
	global_load_dwordx4 v[244:247], v[244:245], off
	s_add_i32 s6, s6, 4
	s_add_i32 s7, s7, 32
	s_waitcnt lgkmcnt(0)
	s_barrier
; #define MFMA(a, b, c) __builtin_amdgcn_mfma_f32_32x32x16_f16(__builtin_bit_cast(h16x8, (a)), __builtin_bit_cast(h16x8, (b)), (c), 0, 0, 0)
; template <int MODE, bool BIG = false> DI void gemm_tile(const Params& p, int tm, int tn, int kv, char* smem) {
;     ...
;     for (int kt = 0; kt < 2 * KT; ++kt) {
;       __syncthreads();
; #pragma unroll
;       for (int i = 0; i < 4; ++i) { const int id = tid + 256 * i; *(uint4*)(As + (id >> 2) * 80 + (id & 3) * 16) = ra[i]; }
; #pragma unroll
;       for (int i = 0; i < 2; ++i) { const int id = tid + 256 * i; *(uint4*)(Bs2 + (id >> 2) * 80 + (id & 3) * 16) = rb[i]; }
;       __syncthreads();
;       if (kt + 1 < 2 * KT) {
;         const int k1 = kt + 1;
; #pragma unroll
;         for (int i = 0; i < 4; ++i) { const int id = tid + 256 * i; ra[i] = load_a<MODE>(p, tma, kv, id >> 2, k1 >> 1, ((k1 & 1) << 2) | (id & 3)); }
; #pragma unroll
;         for (int i = 0; i < 2; ++i) { const int id = tid + 256 * i; rb[i] = load_b<MODE>(p, tn, kv, id >> 2, k1 >> 1, ((k1 & 1) << 2) | (id & 3)); }
;       }
;       {
;         bf16x8 af[2][4], bfr[2][2];
; #pragma unroll
;         for (int s = 0; s < 2; ++s) {
; #pragma unroll
;           for (int i = 0; i < 4; ++i) af[s][i] = *(const bf16x8*)(As + (wm * 128 + i * 32 + r) * 80 + s * 32 + hf * 16);
; #pragma unroll
;           for (int j = 0; j < 2; ++j) bfr[s][j] = *(const bf16x8*)(Bs2 + (wn * 64 + j * 32 + r) * 80 + s * 32 + hf * 16);
;         }
;         __builtin_amdgcn_s_setprio(1);
; #pragma unroll
;         for (int s = 0; s < 2; ++s)
; #pragma unroll
;           for (int i = 0; i < 4; ++i)
; #pragma unroll
;             for (int j = 0; j < 2; ++j) acc[i][j] = MFMA(af[s][i], bfr[s][j], acc[i][j]);
;         __builtin_amdgcn_s_setprio(0);
;       }
;     }
	ds_read_b128 v[180:183], v170 offset:32768
	ds_read_b128 v[188:191], v170 offset:35328
	ds_read_b128 v[196:199], v170 offset:37888
	ds_read_b128 v[204:207], v172 offset:32768
	ds_read_b128 v[212:215], v171 offset:53248
	ds_read_b128 v[220:223], v171 offset:55808
	v_mfma_f32_32x32x16_f16 v[112:127], v[184:187], v[216:219], v[112:127]
	v_mfma_f32_32x32x16_f16 v[96:111], v[184:187], v[224:227], v[96:111]
	v_mfma_f32_32x32x16_f16 v[80:95], v[192:195], v[216:219], v[80:95]
	v_mfma_f32_32x32x16_f16 v[64:79], v[192:195], v[224:227], v[64:79]
	v_mfma_f32_32x32x16_f16 v[48:63], v[200:203], v[216:219], v[48:63]
	v_mfma_f32_32x32x16_f16 v[32:47], v[200:203], v[224:227], v[32:47]
	v_mfma_f32_32x32x16_f16 v[16:31], v[208:211], v[216:219], v[16:31]
	v_mfma_f32_32x32x16_f16 v[0:15], v[208:211], v[224:227], v[0:15]
	s_setprio 0
	ds_read_b128 v[184:187], v170 offset:32800
	ds_read_b128 v[192:195], v170 offset:35360
	ds_read_b128 v[200:203], v170 offset:37920
	ds_read_b128 v[208:211], v172 offset:32800
	ds_read_b128 v[216:219], v171 offset:53280
	ds_read_b128 v[224:227], v171 offset:55840
	s_setprio 1
	s_waitcnt lgkmcnt(6)
	v_mfma_f32_32x32x16_f16 v[112:127], v[180:183], v[212:215], v[112:127]
	s_waitcnt vmcnt(11)
	ds_write_b128 v175, v[132:135]
	v_mfma_f32_32x32x16_f16 v[96:111], v[180:183], v[220:223], v[96:111]
	s_waitcnt vmcnt(10)
	ds_write_b128 v174, v[128:131]
	v_mfma_f32_32x32x16_f16 v[80:95], v[188:191], v[212:215], v[80:95]
	s_waitcnt vmcnt(9)
	ds_write_b128 v177, v[140:143]
	v_mfma_f32_32x32x16_f16 v[64:79], v[188:191], v[220:223], v[64:79]
	s_waitcnt vmcnt(8)
	ds_write_b128 v176, v[136:139]
	v_mfma_f32_32x32x16_f16 v[48:63], v[196:199], v[212:215], v[48:63]
	s_waitcnt vmcnt(7)
	ds_write_b128 v175, v[148:151] offset:20480
	v_mfma_f32_32x32x16_f16 v[32:47], v[196:199], v[220:223], v[32:47]
	s_waitcnt vmcnt(6)
	ds_write_b128 v174, v[144:147] offset:20480
	v_mfma_f32_32x32x16_f16 v[16:31], v[204:207], v[212:215], v[16:31]
	v_mfma_f32_32x32x16_f16 v[0:15], v[204:207], v[220:223], v[0:15]
	s_waitcnt lgkmcnt(0)
	s_barrier
	ds_read_b128 v[180:183], v170
	ds_read_b128 v[188:191], v170 offset:2560
	ds_read_b128 v[196:199], v170 offset:5120
	ds_read_b128 v[204:207], v172
	ds_read_b128 v[212:215], v171 offset:20480
	ds_read_b128 v[220:223], v171 offset:23040
	v_mfma_f32_32x32x16_f16 v[112:127], v[184:187], v[216:219], v[112:127]
	v_mfma_f32_32x32x16_f16 v[96:111], v[184:187], v[224:227], v[96:111]
	v_mfma_f32_32x32x16_f16 v[80:95], v[192:195], v[216:219], v[80:95]
	v_mfma_f32_32x32x16_f16 v[64:79], v[192:195], v[224:227], v[64:79]
	v_mfma_f32_32x32x16_f16 v[48:63], v[200:203], v[216:219], v[48:63]
	v_mfma_f32_32x32x16_f16 v[32:47], v[200:203], v[224:227], v[32:47]
	v_mfma_f32_32x32x16_f16 v[16:31], v[208:211], v[216:219], v[16:31]
	v_mfma_f32_32x32x16_f16 v[0:15], v[208:211], v[224:227], v[0:15]
	s_setprio 0
	ds_read_b128 v[184:187], v170 offset:32
	ds_read_b128 v[192:195], v170 offset:2592
	ds_read_b128 v[200:203], v170 offset:5152
	ds_read_b128 v[208:211], v172 offset:32
	ds_read_b128 v[216:219], v171 offset:20512
	ds_read_b128 v[224:227], v171 offset:23072
	s_setprio 1
	s_waitcnt lgkmcnt(6)
	v_mfma_f32_32x32x16_f16 v[112:127], v[180:183], v[212:215], v[112:127]
	s_waitcnt vmcnt(5)
	ds_write_b128 v175, v[232:235] offset:32768
	v_mfma_f32_32x32x16_f16 v[96:111], v[180:183], v[220:223], v[96:111]
	s_waitcnt vmcnt(4)
	ds_write_b128 v174, v[228:231] offset:32768
	v_mfma_f32_32x32x16_f16 v[80:95], v[188:191], v[212:215], v[80:95]
	s_waitcnt vmcnt(3)
	ds_write_b128 v177, v[240:243] offset:32768
	v_mfma_f32_32x32x16_f16 v[64:79], v[188:191], v[220:223], v[64:79]
	s_waitcnt vmcnt(2)
	ds_write_b128 v176, v[236:239] offset:32768
	v_mfma_f32_32x32x16_f16 v[48:63], v[196:199], v[212:215], v[48:63]
	s_waitcnt vmcnt(1)
	ds_write_b128 v175, v[248:251] offset:53248
	v_mfma_f32_32x32x16_f16 v[32:47], v[196:199], v[220:223], v[32:47]
	s_waitcnt vmcnt(0)
	ds_write_b128 v174, v[244:247] offset:53248
	v_mfma_f32_32x32x16_f16 v[16:31], v[204:207], v[212:215], v[16:31]
	v_mfma_f32_32x32x16_f16 v[0:15], v[204:207], v[220:223], v[0:15]
	s_waitcnt lgkmcnt(0)
	s_barrier
	ds_read_b128 v[180:183], v170 offset:32768
	ds_read_b128 v[188:191], v170 offset:35328
	ds_read_b128 v[196:199], v170 offset:37888
	ds_read_b128 v[204:207], v172 offset:32768
	ds_read_b128 v[212:215], v171 offset:53248
	ds_read_b128 v[220:223], v171 offset:55808
	v_mfma_f32_32x32x16_f16 v[112:127], v[184:187], v[216:219], v[112:127]
	v_mfma_f32_32x32x16_f16 v[96:111], v[184:187], v[224:227], v[96:111]
	v_mfma_f32_32x32x16_f16 v[80:95], v[192:195], v[216:219], v[80:95]
	v_mfma_f32_32x32x16_f16 v[64:79], v[192:195], v[224:227], v[64:79]
	v_mfma_f32_32x32x16_f16 v[48:63], v[200:203], v[216:219], v[48:63]
	v_mfma_f32_32x32x16_f16 v[32:47], v[200:203], v[224:227], v[32:47]
	v_mfma_f32_32x32x16_f16 v[16:31], v[208:211], v[216:219], v[16:31]
	v_mfma_f32_32x32x16_f16 v[0:15], v[208:211], v[224:227], v[0:15]
	s_setprio 0
	ds_read_b128 v[184:187], v170 offset:32800
	ds_read_b128 v[192:195], v170 offset:35360
	ds_read_b128 v[200:203], v170 offset:37920
	ds_read_b128 v[208:211], v172 offset:32800
	ds_read_b128 v[216:219], v171 offset:53280
	ds_read_b128 v[224:227], v171 offset:55840
	s_setprio 1
	s_waitcnt lgkmcnt(6)
	v_mfma_f32_32x32x16_f16 v[112:127], v[180:183], v[212:215], v[112:127]
	v_mfma_f32_32x32x16_f16 v[96:111], v[180:183], v[220:223], v[96:111]
	v_mfma_f32_32x32x16_f16 v[80:95], v[188:191], v[212:215], v[80:95]
	v_mfma_f32_32x32x16_f16 v[64:79], v[188:191], v[220:223], v[64:79]
	v_mfma_f32_32x32x16_f16 v[48:63], v[196:199], v[212:215], v[48:63]
	v_mfma_f32_32x32x16_f16 v[32:47], v[196:199], v[220:223], v[32:47]
	v_mfma_f32_32x32x16_f16 v[16:31], v[204:207], v[212:215], v[16:31]
	v_mfma_f32_32x32x16_f16 v[0:15], v[204:207], v[220:223], v[0:15]
	s_waitcnt lgkmcnt(0)
	v_mfma_f32_32x32x16_f16 v[112:127], v[184:187], v[216:219], v[112:127]
	v_mfma_f32_32x32x16_f16 v[96:111], v[184:187], v[224:227], v[96:111]
	v_mfma_f32_32x32x16_f16 v[80:95], v[192:195], v[216:219], v[80:95]
	v_mfma_f32_32x32x16_f16 v[64:79], v[192:195], v[224:227], v[64:79]
	v_mfma_f32_32x32x16_f16 v[48:63], v[200:203], v[216:219], v[48:63]
	v_mfma_f32_32x32x16_f16 v[32:47], v[200:203], v[224:227], v[32:47]
	v_mfma_f32_32x32x16_f16 v[16:31], v[208:211], v[216:219], v[16:31]
	v_mfma_f32_32x32x16_f16 v[0:15], v[208:211], v[224:227], v[0:15]
	s_setprio 0
	v_ashrrev_i32_e32 v130, 1, v169
	v_lshlrev_b32_e32 v131, 6, v169
	v_mul_lo_u32 v129, v130, s9
	v_and_b32_e32 v131, 64, v131
	v_lshl_add_u32 v129, v131, 2, v129
	v_or_b32_e32 v132, s3, v131
	v_lshlrev_b32_e32 v131, 8, v167
	v_lshl_or_b32 v131, v168, 2, v131
	v_ashrrev_i32_e32 v132, 5, v132
	v_ashrrev_i32_e32 v128, 7, v169
	v_add_u32_e32 v130, s2, v130
	v_mad_u32_u24 v131, v166, s10, v131
	v_or_b32_e32 v133, 1, v132
	s_mov_b32 s15, 0
	s_mov_b64 s[2:3], -1
	s_branch .LBB0_981
